# adds: static s_setprio 1 for waves 4-7 across the attention phase (flash and memory units) as well
# baseline (speedup 1.0000x reference)
; #define LAS __attribute__((address_space(3)))
; __device__ __forceinline__ int lane_id_hw() { int l; asm volatile("v_mbcnt_lo_u32_b32 %0, -1, 0\n\tv_mbcnt_hi_u32_b32 %0, -1, %0" : "=v"(l)); return l; }
; __device__ __forceinline__ void make_frame(Frame& F, LAS unsigned char* lds, int wave_s) {
;     ...
;     F.G = gridDim.x; { const int bx = blockIdx.x; F.vcu = (F.G % 8 == 0) ? (bx % 8) * (F.G / 8) + bx / 8 : bx; }
;     LAS unsigned char* lds = F.lds; const int tid = F.tid, G = F.G;
;     int tpar = 0;
;     const int wid = F.wave;
;     if (FLASH_NA && (mask & 1)) for (int i = 0;; ++i) {
;         const int u = i * G + F.vcu; if (u >= 1152) break;
;         const int bh = u >> 3, blk = u & 7, b = bh / 12, h = bh % 12;
;         const int ln = lane_id_hw(), r32 = ln & 31, hi = ln >> 5;
;         fa::FlashUnit U; U.C = 0.08838834764831845f * LOG2E; U.tblo = fa::OFF_TBL + tpar * 4096; tpar ^= 1;
;         const int rb = blk >> 2, cb = blk & 3, lo = rb ? 12 : 0; U.NT = 10;
.LBB0_466:
	s_andn2_b64 vcc, exec, s[4:5]
	v_readlane_b32 s4, v255, 47
	s_mul_i32 s89, s4, 12
	s_cbranch_vccnz .LBB0_547
	v_readlane_b32 s98, v255, 4
	s_nop 3
	s_cmp_lg_u32 s98, 0
	s_cbranch_scc0 .Lprio_skip_attn
	s_setprio 1
.Lprio_skip_attn:
	v_readlane_b32 s4, v254, 0
	v_readlane_b32 s8, v254, 9
	v_readlane_b32 s5, v254, 1
	v_readlane_b32 s9, v254, 10
	s_waitcnt lgkmcnt(0)
	v_mbcnt_lo_u32_b32 v0, -1, 0
	v_mbcnt_hi_u32_b32 v0, -1, v0
	s_load_dword s90, s[8:9], 0x0
	s_mov_b32 s18, s2
	s_waitcnt lgkmcnt(0)
	s_and_b32 s8, s90, 7
	s_cmp_lg_u32 s8, 0
	s_cbranch_scc1 .LBB0_469
	s_ashr_i32 s8, s90, 3
	v_readlane_b32 s9, v255, 15
	s_mul_i32 s8, s8, s9
	v_readlane_b32 s9, v255, 3
	s_add_i32 s18, s8, s9

; #define RUN(k) (probing ? (probe_phase == (k)) : IN(pb + (k) - 1))
; #define SEAM2(k) do { if (probing || (IN(pb + (k) - 1) && IN(pb + (k)))) xcd_barrier(bar, wave_s == 0 && lane_id_hw() == 0); } while (0)
; __global__ void __launch_bounds__(NWAVES * 64, 2) fwd(Args args) {
;     ...
;         if (RUN(2)) { Frame F; make_frame(F, lds, wave_s); attention_phase(F, l); if (!(FLASH_NA && FLASH_SW && FLASH_MEM)) naive_attention(F, l); if (!GATES_FP8) SEAM2(2); }
;         if (GATES_FP8 && RUN(2)) {
.LBB0_547:
	s_setprio 0
	v_readlane_b32 s4, v255, 49
	v_readlane_b32 s5, v255, 50
	s_and_b64 vcc, exec, s[4:5]
	s_cbranch_vccz .LBB0_549
	v_readlane_b32 s4, v255, 47
	s_mul_i32 s4, s4, 5
	s_add_i32 s8, s4, 2
	v_readlane_b32 s36, v254, 5
	v_readlane_b32 s37, v254, 6
	s_cmp_le_i32 s36, s8
	s_cselect_b64 s[4:5], -1, 0
	s_cmp_lt_i32 s8, s37
	s_cselect_b64 s[8:9], -1, 0
	v_readlane_b32 s38, v254, 7
	v_readlane_b32 s39, v254, 8
	s_and_b64 s[4:5], s[4:5], s[8:9]
	s_cbranch_execz .LBB0_550
	s_branch .LBB0_551
